# P4 chain loop: V-row loads with fixed per-thread offsets, constant LDS address adds folded into ds offsets, g loads in saddr form, dead parity toggles removed
# speedup vs baseline: 1.0053x; 1.0006x over previous
.Lp4n_tab:
	v_mbcnt_lo_u32_b32 v229, -1, 0
	v_mbcnt_hi_u32_b32 v229, -1, v229
	v_and_b32_e32 v230, s61, v229
	v_lshrrev_b32_e32 v231, s62, v229
	v_lshrrev_b32_e32 v232, 1, v231
	v_add_u32_e32 v232, s59, v232
	v_and_b32_e32 v232, 7, v232
	v_add_u32_e32 v233, s60, v231
	v_and_b32_e32 v233, 1, v233
	v_sub_u32_e32 v234, s61, v230
	v_cmp_eq_u32_e32 vcc, 1, v233
	s_nop 1
	v_cndmask_b32_e32 v235, v230, v234, vcc
	v_add_u32_e32 v235, s64, v235
	v_cmp_eq_u32_e32 vcc, s61, v230
	s_nop 1
	v_cndmask_b32_e64 v236, 0, 1, vcc
	v_lshlrev_b32_e32 v237, 9, v232
	v_or_b32_e32 v220, v235, v237
	v_lshlrev_b32_e32 v237, 12, v233
	v_or_b32_e32 v220, v220, v237
	s_lshl_b32 s45, s57, 13
	s_lshl_b32 s46, s58, 15
	s_or_b32 s45, s45, s46
	s_lshl_b32 s46, s63, 20
	s_or_b32 s45, s45, s46
	v_or_b32_e32 v220, s45, v220
	v_lshlrev_b32_e32 v237, 21, v236
	v_or_b32_e32 v220, v220, v237
	v_lshlrev_b32_e32 v237, 22, v230
	v_or_b32_e32 v220, v220, v237
	v_lshl_add_u32 v237, v235, 3, v232
	v_lshlrev_b32_e32 v221, 14, v237
	v_lshlrev_b32_e32 v238, 8, v233
	v_lshl_add_u32 v224, v237, 10, v238
	v_lshlrev_b32_e32 v238, 8, v232
	v_lshl_add_u32 v222, v235, 17, v238
	s_mov_b32 s45, 0xc0000
	v_mul_lo_u32 v237, v235, s45
	s_lshl_b32 s46, s57, 6
	s_sub_u32 s46, s46, 0x5000
	v_add_u32_e32 v238, s46, v238
	v_add_u32_e32 v223, v237, v238
	s_mov_b32 s45, 0x60000
	v_mul_lo_u32 v237, v235, s45
	v_lshlrev_b32_e32 v238, 10, v233
	v_lshl_add_u32 v238, v232, 7, v238
	s_lshl_b32 s46, s57, 5
	v_add_u32_e32 v238, s46, v238
	v_add_u32_e32 v227, v237, v238
	v_lshlrev_b32_e32 v228, 6, v235
	v_mov_b32_e32 v225, s65
	v_mov_b32_e32 v226, s66
	s_mov_b32 s99, 0
	v_add_u32_e32 v247, 0x3000, v120
	v_add_u32_e32 v248, 0x6000, v120
	v_add_u32_e32 v249, 0x9000, v120
	v_lshlrev_b32_e32 v239, 4, v0
	v_add_u32_e32 v240, 0x2000, v239
	v_mov_b32_e32 v241, v118
	v_add_u32_e32 v242, 0x10000, v118
	s_mov_b32 s100, 0xbfb8aa3b
	s_mov_b32 s101, 0xbfb8aa3b
	s_nop 1
	v_readlane_b32 s41, v220, 0
	v_readlane_b32 s42, v220, 1
	v_readlane_b32 s43, v220, 2

.Lp4n_stg_A:
	s_cmp_lt_u32 s99, 63
	s_cbranch_scc0 .Lp4n_premid_A
	s_bfe_u32 s45, s42, 0x1000c
	s_cmp_eq_u32 s45, 0
	s_cselect_b64 vcc, -1, 0
	v_cndmask_b32_e32 v106, v162, v161, vcc
	v_cndmask_b32_e32 v107, v164, v163, vcc
	v_cndmask_b32_e32 v108, v166, v165, vcc
	v_cndmask_b32_e32 v109, v168, v167, vcc
	s_waitcnt vmcnt(11)
	ds_write_b128 v169, v[34:37] offset:17408
	s_waitcnt vmcnt(10)
	ds_write_b128 v169, v[38:41] offset:26112
	ds_write_b128 v170, v[26:29]
	ds_write_b128 v170, v[30:33] offset:9216
	s_waitcnt vmcnt(9)
	v_and_b32_e32 v102, v42, v106
	v_and_b32_e32 v103, v43, v107
	v_and_b32_e32 v104, v44, v108
	v_and_b32_e32 v105, v45, v109
	ds_write_b128 v171, v[102:105] offset:17408
	s_waitcnt vmcnt(8)
	v_and_b32_e32 v102, v46, v106
	v_and_b32_e32 v103, v47, v107
	v_and_b32_e32 v104, v48, v108
	v_and_b32_e32 v105, v49, v109
	s_bfe_u32 s45, s42, 0x60016
	s_cmp_lg_u32 s45, 0
	ds_write_b128 v172, v[102:105] offset:9216
	s_cbranch_scc1 .Lp4n_cwkeep_A
	s_waitcnt vmcnt(4)
	v_mov_b64_e32 v[84:85], v[24:25]
	v_mov_b64_e32 v[88:89], v[20:21]
	v_mov_b64_e32 v[92:93], v[16:17]
	v_mov_b64_e32 v[96:97], v[12:13]
	v_mov_b64_e32 v[82:83], v[22:23]
	v_mov_b64_e32 v[86:87], v[18:19]
	v_mov_b64_e32 v[90:91], v[14:15]
	v_mov_b64_e32 v[94:95], v[10:11]

.Lp4n_nocwn_A:
	s_cmp_lt_u32 s99, 61
	s_cbranch_scc0 .Lp4n_premid_A
	s_add_u32 s46, s99, 3
	s_nop 3
	v_readlane_b32 s8, v221, s46
	v_readlane_b32 s88, v222, s46
	v_readlane_b32 s20, v223, s46
	v_readlane_b32 s47, v224, s46
	v_readlane_b32 s76, v225, s46
	v_readlane_b32 s77, v226, s46
	v_readlane_b32 s22, v228, s46
	v_readlane_b32 s44, v220, s46
	s_add_u32 s88, s72, s88
	s_addc_u32 s89, s73, 0
	s_add_u32 s90, s78, s8
	s_addc_u32 s91, s79, 0
	s_add_u32 s92, s80, s8
	s_addc_u32 s93, s81, 0
	global_load_dwordx4 v[26:29], v239, s[90:91]
	global_load_dwordx4 v[30:33], v240, s[90:91]
	global_load_dwordx4 v[34:37], v241, s[88:89]
	global_load_dwordx4 v[38:41], v242, s[88:89]
	global_load_dwordx4 v[42:45], v239, s[92:93]
	global_load_dwordx4 v[46:49], v240, s[92:93]
	s_ashr_i32 s89, s20, 31
	s_add_u32 s88, s0, s20
	s_addc_u32 s89, s1, s89
	s_bfe_u32 s45, s44, 0x60016
	s_cmp_eq_u32 s45, 0
	s_cbranch_scc1 .Lp4n_vedge_A
	s_bfe_u32 s45, s44, 0x10015
	s_cmp_lg_u32 s45, 0
	s_cbranch_scc1 .Lp4n_vedge_A
	global_load_dwordx2 v[128:129], v120, s[88:89]
	global_load_dwordx2 v[130:131], v247, s[88:89]
	global_load_dwordx2 v[132:133], v248, s[88:89]
	global_load_dwordx2 v[136:137], v249, s[88:89]
	s_branch .Lp4n_vdone_A

.Lp4n_vdone_A:
	s_add_u32 s8, s30, s47
	s_addc_u32 s9, s31, 0
	global_load_dword v175, v122, s[8:9] offset:512
	v_mov_b32_e32 v177, 0
	v_mov_b32_e32 v176, 0
	s_and_saveexec_b64 s[20:21], s[4:5]
	s_cbranch_execz .Lp4n_gdone_A
	global_load_dword v176, v124, s[8:9]
	global_load_dword v177, v124, s[8:9] offset:512

.Lp4n_end_A:
	s_waitcnt lgkmcnt(0)
	s_barrier
	s_cmp_lt_u32 s99, 63
	s_cbranch_scc0 .Lp4n_exit
	s_add_u32 s99, s99, 1
	s_mov_b32 s41, s42
	s_mov_b32 s42, s43
	s_mov_b32 s43, s44
.Lp4n_top_B:
	s_cmp_lt_u32 s99, 63
	s_cselect_b64 s[10:11], -1, 0
	ds_read_b128 v[2:5], v193 offset:31232
	ds_read_b128 v[6:9], v192 offset:48640
	ds_read_b128 v[110:113], v192 offset:48704
	ds_read_b128 v[114:117], v193 offset:31296
	ds_read_b128 v[198:201], v190 offset:17408
	ds_read_b128 v[202:205], v190 offset:17472
	s_waitcnt lgkmcnt(0)
	v_mfma_f32_16x16x32_bf16 v[2:5], v[2:5], v[6:9], 0
	s_mov_b32 s87, 0x1d900
	s_waitcnt lgkmcnt(1)
	v_mfma_f32_16x16x32_bf16 v[6:9], v[198:201], v[6:9], 0
	v_mfma_f32_16x16x32_bf16 v[2:5], v[114:117], v[110:113], v[2:5]
	ds_read_b128 v[114:117], v193 offset:31360
	ds_read_b128 v[198:201], v192 offset:48768
	s_waitcnt lgkmcnt(2)
	v_mfma_f32_16x16x32_bf16 v[6:9], v[202:205], v[110:113], v[6:9]
	ds_read_b128 v[110:113], v193 offset:31424
	ds_read_b128 v[202:205], v192 offset:48832
	s_waitcnt lgkmcnt(2)
	v_mfma_f32_16x16x32_bf16 v[2:5], v[114:117], v[198:201], v[2:5]
	ds_read_b128 v[114:117], v190 offset:17536
	ds_read_b128 v[206:209], v190 offset:17600
	v_lshl_add_u32 v159, v189, 2, s87
	s_waitcnt lgkmcnt(2)
	v_mfma_f32_16x16x32_bf16 v[2:5], v[110:113], v[202:205], v[2:5]
	ds_read_b128 v[110:113], v159 offset:512
	s_waitcnt lgkmcnt(2)
	v_mfma_f32_16x16x32_bf16 v[6:9], v[114:117], v[198:201], v[6:9]
	s_nop 4
	v_sub_f32_e32 v5, v101, v5
	v_sub_f32_e32 v4, v100, v4
	v_sub_f32_e32 v3, v99, v3
	v_sub_f32_e32 v2, v98, v2
	v_cvt_pk_bf16_f32 v114, v2, v3
	s_waitcnt lgkmcnt(0)
	v_pk_mul_f32 v[2:3], v[2:3], v[110:111]
	v_cvt_pk_bf16_f32 v115, v4, v5
	v_pk_mul_f32 v[4:5], v[4:5], v[112:113]
	v_cvt_pk_bf16_f32 v2, v2, v3
	v_cvt_pk_bf16_f32 v3, v4, v5
	ds_write2st64_b64 v194, v[114:115], v[2:3] offset0:112 offset1:121
	ds_read_b128 v[110:113], v159
	v_mfma_f32_16x16x32_bf16 v[114:117], v[206:209], v[202:205], v[6:9]
.Lp4n_stg_B:
	s_cmp_lt_u32 s99, 63
	s_cbranch_scc0 .Lp4n_premid_B
	s_bfe_u32 s45, s42, 0x1000c
	s_cmp_eq_u32 s45, 0
	s_cselect_b64 vcc, -1, 0
	v_cndmask_b32_e32 v6, v162, v161, vcc
	v_cndmask_b32_e32 v7, v164, v163, vcc
	v_cndmask_b32_e32 v8, v166, v165, vcc
	v_cndmask_b32_e32 v9, v168, v167, vcc
	s_waitcnt vmcnt(11)
	ds_write_b128 v169, v[58:61]
	s_waitcnt vmcnt(10)
	ds_write_b128 v169, v[62:65] offset:8704
	ds_write_b128 v170, v[50:53]
	ds_write_b128 v170, v[54:57] offset:9216
	s_waitcnt vmcnt(9)
	v_and_b32_e32 v2, v66, v6
	v_and_b32_e32 v3, v67, v7
	v_and_b32_e32 v4, v68, v8
	v_and_b32_e32 v5, v69, v9
	ds_write_b128 v171, v[2:5] offset:17408
	s_waitcnt vmcnt(8)
	v_and_b32_e32 v2, v70, v6
	v_and_b32_e32 v3, v71, v7
	v_and_b32_e32 v4, v72, v8
	v_and_b32_e32 v5, v73, v9
	s_bfe_u32 s45, s42, 0x60016
	s_cmp_lg_u32 s45, 0
	ds_write_b128 v172, v[2:5]
	s_cbranch_scc1 .Lp4n_cwkeep_B
	s_waitcnt vmcnt(4)
	v_mov_b64_e32 v[84:85], v[24:25]
	v_mov_b64_e32 v[88:89], v[20:21]
	v_mov_b64_e32 v[92:93], v[16:17]
	v_mov_b64_e32 v[96:97], v[12:13]
	v_mov_b64_e32 v[82:83], v[22:23]
	v_mov_b64_e32 v[86:87], v[18:19]
	v_mov_b64_e32 v[90:91], v[14:15]
	v_mov_b64_e32 v[94:95], v[10:11]

.Lp4n_nocwn_B:
	s_cmp_lt_u32 s99, 61
	s_cbranch_scc0 .Lp4n_premid_B
	s_add_u32 s46, s99, 3
	s_nop 3
	v_readlane_b32 s8, v221, s46
	v_readlane_b32 s88, v222, s46
	v_readlane_b32 s20, v223, s46
	v_readlane_b32 s47, v224, s46
	v_readlane_b32 s76, v225, s46
	v_readlane_b32 s77, v226, s46
	v_readlane_b32 s22, v228, s46
	v_readlane_b32 s44, v220, s46
	s_add_u32 s88, s72, s88
	s_addc_u32 s89, s73, 0
	s_add_u32 s90, s78, s8
	s_addc_u32 s91, s79, 0
	s_add_u32 s92, s80, s8
	s_addc_u32 s93, s81, 0
	global_load_dwordx4 v[50:53], v239, s[90:91]
	global_load_dwordx4 v[54:57], v240, s[90:91]
	global_load_dwordx4 v[58:61], v241, s[88:89]
	global_load_dwordx4 v[62:65], v242, s[88:89]
	global_load_dwordx4 v[66:69], v239, s[92:93]
	global_load_dwordx4 v[70:73], v240, s[92:93]
	s_ashr_i32 s89, s20, 31
	s_add_u32 s88, s0, s20
	s_addc_u32 s89, s1, s89
	s_bfe_u32 s45, s44, 0x60016
	s_cmp_eq_u32 s45, 0
	s_cbranch_scc1 .Lp4n_vedge_B
	s_bfe_u32 s45, s44, 0x10015
	s_cmp_lg_u32 s45, 0
	s_cbranch_scc1 .Lp4n_vedge_B
	global_load_dwordx2 v[134:135], v120, s[88:89]
	global_load_dwordx2 v[138:139], v247, s[88:89]
	global_load_dwordx2 v[140:141], v248, s[88:89]
	global_load_dwordx2 v[142:143], v249, s[88:89]
	s_branch .Lp4n_vdone_B

.Lp4n_vdone_B:
	s_add_u32 s8, s30, s47
	s_addc_u32 s9, s31, 0
	global_load_dword v181, v122, s[8:9] offset:512
	v_mov_b32_e32 v185, 0
	v_mov_b32_e32 v184, 0
	s_and_saveexec_b64 s[20:21], s[4:5]
	s_cbranch_execz .Lp4n_gdone_B
	global_load_dword v184, v124, s[8:9]
	global_load_dword v185, v124, s[8:9] offset:512

.Lp4n_premid_B:
.Lp4n_mid_B:
	s_waitcnt lgkmcnt(0)
	s_barrier
	v_mov_b32_e32 v2, s87
	ds_read_b32 v198, v2 offset:768
	ds_read_b128 v[2:5], v196 offset:61952
	ds_read_b128 v[6:9], v196 offset:64256
	s_waitcnt lgkmcnt(2)
	v_pk_mul_f32 v[104:105], v[104:105], v[198:199] op_sel_hi:[1,0]
	v_pk_mul_f32 v[102:103], v[102:103], v[198:199] op_sel_hi:[1,0]
	v_pk_mul_f32 v[108:109], v[108:109], v[198:199] op_sel_hi:[1,0]
	v_pk_mul_f32 v[106:107], v[106:107], v[198:199] op_sel_hi:[1,0]
	s_waitcnt lgkmcnt(1)
	v_mfma_f32_16x16x32_bf16 v[102:105], v[74:77], v[2:5], v[102:105]
	ds_read_b128 v[2:5], v196 offset:62016
	s_waitcnt lgkmcnt(1)
	v_mfma_f32_16x16x32_bf16 v[106:109], v[74:77], v[6:9], v[106:109]
	v_readlane_b32 s8, v227, s99
	s_lshl_b32 s8, s8, 1
	s_add_u32 s8, s0, s8
	s_addc_u32 s9, s1, 0
	s_waitcnt lgkmcnt(0)
	v_mfma_f32_16x16x32_bf16 v[2:5], v[78:81], v[2:5], v[102:105]
	s_nop 2
	ds_read_b128 v[102:105], v196 offset:64320
	ds_read_b128 v[198:201], v191 offset:9216
	ds_read_b128 v[202:205], v187 offset:57344
	s_waitcnt lgkmcnt(2)
	v_mfma_f32_16x16x32_bf16 v[6:9], v[78:81], v[102:105], v[106:109]
	v_mul_f32_e64 v104, v116, v112
	v_mul_f32_e64 v105, v117, v113
	v_pk_mul_f32 v[102:103], v[114:115], v[110:111]
	ds_read_b128 v[110:113], v191 offset:9280
	ds_read_b128 v[106:109], v187 offset:57408
	s_waitcnt lgkmcnt(2)
	v_mfma_f32_16x16x32_bf16 v[102:105], v[198:201], v[202:205], v[102:105]
	s_bfe_u32 s45, s41, 0x10015
	s_cmp_eq_u32 s45, 0
	s_waitcnt lgkmcnt(0)
	v_mfma_f32_16x16x32_bf16 v[102:105], v[110:113], v[106:109], v[102:105]
	s_nop 7
	v_cvt_pk_bf16_f32 v102, v102, s0
	global_store_short v243, v102, s[8:9]
	v_cvt_pk_bf16_f32 v108, v103, s0
	global_store_short v244, v108, s[8:9]
	v_cvt_pk_bf16_f32 v104, v104, s0
	global_store_short v245, v104, s[8:9]
	v_cvt_pk_bf16_f32 v103, v105, s0
	global_store_short v246, v103, s[8:9]
	s_cbranch_scc1 .Lp4n_sjoin_B
	s_bfe_u32 s45, s41, 0x10014
	s_cmp_lg_u32 s45, 0
	s_cbranch_scc1 .Lp4n_nosst_B
	s_bfe_u32 s8, s41, 0x5000f
	s_lshl_b32 s8, s8, 4
	s_bfe_u32 s9, s41, 0x1000c
	s_lshl_b32 s9, s9, 3
	s_bfe_u32 s14, s41, 0x30009
	s_add_i32 s8, s14, s8
	s_bfe_u32 s14, s41, 0x2000d
	s_lshl_b32 s14, s14, 5
	s_add_i32 s8, s8, s9
	s_ashr_i32 s9, s8, 31
	s_lshl_b64 s[8:9], s[8:9], 16
	s_add_u32 s20, s72, s8
	s_addc_u32 s21, s73, s9
	s_lshl_b64 s[8:9], s[14:15], 2
	s_add_u32 s8, s20, s8
	s_addc_u32 s9, s21, s9
	v_lshl_add_u64 v[102:103], s[8:9], 0, v[126:127]
	v_lshl_add_u64 v[102:103], v[102:103], 0, s[18:19]
	v_lshl_add_u64 v[104:105], v[102:103], 0, v[144:145]
	v_lshl_add_u64 v[106:107], v[102:103], 0, v[146:147]
	v_lshl_add_u64 v[108:109], v[102:103], 0, v[148:149]
	v_lshl_add_u64 v[102:103], v[102:103], 0, v[150:151]
	global_store_dword v[104:105], v2, off
	global_store_dword v[106:107], v3, off
	global_store_dword v[108:109], v4, off
	global_store_dword v[102:103], v5, off
	global_store_dword v[104:105], v6, off offset:64
	global_store_dword v[106:107], v7, off offset:64
	global_store_dword v[108:109], v8, off offset:64
	global_store_dword v[102:103], v9, off offset:64

.Lp4n_end_B:
	s_waitcnt lgkmcnt(0)
	s_barrier
	s_cmp_lt_u32 s99, 63
	s_cbranch_scc0 .Lp4n_exit
	s_add_u32 s99, s99, 1
	s_mov_b32 s41, s42
	s_mov_b32 s42, s43
	s_mov_b32 s43, s44
	s_branch .Lp4n_top_A
